# 64-byte alignment of the six GEMM K-loop heads (code placement), on top of q7
# speedup vs baseline: 1.0073x; 1.0073x over previous
;     __device__ bool next(int i, Unit& u) const { Unit t; if (!T.next(i / 3, t)) return false; u.pm = t.pm; u.pn = (i % 3) * 4 + t.pn; return true; }
;     __device__ __forceinline__ size_t aoff(const Unit& u) const { const int br = u.pn >> 2; return (size_t)(br == 0 ? 0 : (br == 1 ? 256 : 768)) * 2; }
;     __device__ __forceinline__ int nt(const Unit& u, int) const { return (u.pn >> 2) == 0 ? 4 : 8; }
; template <class Epi, class Sched, bool ALIGN_EPI = false, bool SP2 = false>
; __device__ __forceinline__ void gemm_phase(PG8_LAS unsigned char* lds, const Gemm g, const Sched& S, const Epi& E, const int lda) {
;     ...
;         const bool has_next = S.next(ui + 1, nxt);
;         const char* nA = has_next ? (const char*)gA + (size_t)nxt.pm * tstepA + S.aoff(nxt) : cA; const char* nB = has_next ? (const char*)gB + (size_t)nxt.pn * tstep : cB;
;         for (int t = 0; t < nt; t += 2) {
;             const bool last = (t == nt - 2);
;             const char* a1 = cA + (size_t)(t + 1) * kstep;
;             const char* a2 = last ? nA : cA + (size_t)(t + 2) * kstep; const char* b2 = last ? nB : cB + (size_t)(t + 2) * kstep;
;             const char* a3 = a2 + kstep; const char* b3 = b2 + kstep;
;     ...
; #pragma unroll
;         for (int a = 0; a < 2; ++a)
; #pragma unroll
;             for (int b = 0; b < 2; ++b)
; #pragma unroll
;                 for (int m = 0; m < 4; ++m)
; #pragma unroll
;                     for (int n = 0; n < 2; ++n) acc[a][b][m][n] = (f32x4){0.f, 0.f, 0.f, 0.f};
;         cur = nxt; cA = nA; cB = nB; ++ui; nt = S.nt(cur, K / BK);
.LBB0_151:
	s_ashr_i32 s67, s66, 31
	s_lshl_b64 s[24:25], s[66:67], 19
	s_add_u32 s68, s50, s24
	s_addc_u32 s69, s51, s25
	s_and_b64 s[24:25], s[42:43], exec
	s_cselect_b32 s63, s69, s73
	s_cselect_b32 s67, s68, s72
	s_ashr_i32 s65, s64, 31
	s_lshl_b64 s[24:25], s[64:65], 19
	s_add_u32 s70, s52, s24
	s_addc_u32 s71, s53, s25
	s_and_b64 s[24:25], s[42:43], exec
	s_cselect_b32 s65, s71, s75
	s_cselect_b32 s24, s70, s74
	s_add_u32 s25, s74, 0x100
	s_addc_u32 s26, s75, 0
	s_add_u32 s72, s72, 0x40080
	v_mov_b32_e32 v0, 0
	s_addc_u32 s73, s73, 0
	s_mov_b32 s27, -2
	v_mov_b32_e32 v1, v0
	v_mov_b32_e32 v2, v0
	s_waitcnt lgkmcnt(0)
	v_mov_b32_e32 v3, v0
	v_mov_b32_e32 v32, v0
	v_mov_b32_e32 v33, v0
	v_mov_b32_e32 v34, v0
	v_mov_b32_e32 v35, v0
	v_mov_b32_e32 v4, v0
	v_mov_b32_e32 v5, v0
	v_mov_b32_e32 v6, v0
	v_mov_b32_e32 v7, v0
	v_mov_b32_e32 v36, v0
	v_mov_b32_e32 v37, v0
	v_mov_b32_e32 v38, v0
	v_mov_b32_e32 v39, v0
	v_mov_b32_e32 v8, v0
	v_mov_b32_e32 v9, v0
	v_mov_b32_e32 v10, v0
	v_mov_b32_e32 v11, v0
	v_mov_b32_e32 v40, v0
	v_mov_b32_e32 v41, v0
	v_mov_b32_e32 v42, v0
	v_mov_b32_e32 v43, v0
	v_mov_b32_e32 v12, v0
	v_mov_b32_e32 v13, v0
	v_mov_b32_e32 v14, v0
	v_mov_b32_e32 v15, v0
	v_mov_b32_e32 v44, v0
	v_mov_b32_e32 v45, v0
	v_mov_b32_e32 v46, v0
	v_mov_b32_e32 v47, v0
	v_mov_b32_e32 v64, v0
	v_mov_b32_e32 v65, v0
	v_mov_b32_e32 v66, v0
	v_mov_b32_e32 v67, v0
	v_mov_b32_e32 v96, v0
	v_mov_b32_e32 v97, v0
	v_mov_b32_e32 v98, v0
	v_mov_b32_e32 v99, v0
	v_mov_b32_e32 v68, v0
	v_mov_b32_e32 v69, v0
	v_mov_b32_e32 v70, v0
	v_mov_b32_e32 v71, v0
	v_mov_b32_e32 v100, v0
	v_mov_b32_e32 v101, v0
	v_mov_b32_e32 v102, v0
	v_mov_b32_e32 v103, v0
	v_mov_b32_e32 v72, v0
	v_mov_b32_e32 v73, v0
	v_mov_b32_e32 v74, v0
	v_mov_b32_e32 v75, v0
	v_mov_b32_e32 v104, v0
	v_mov_b32_e32 v105, v0
	v_mov_b32_e32 v106, v0
	v_mov_b32_e32 v107, v0
	v_mov_b32_e32 v76, v0
	v_mov_b32_e32 v77, v0
	v_mov_b32_e32 v78, v0
	v_mov_b32_e32 v79, v0
	v_mov_b32_e32 v108, v0
	v_mov_b32_e32 v109, v0
	v_mov_b32_e32 v110, v0
	v_mov_b32_e32 v111, v0
	v_mov_b32_e32 v16, v0
	v_mov_b32_e32 v17, v0
	v_mov_b32_e32 v18, v0
	v_mov_b32_e32 v19, v0
	v_mov_b32_e32 v48, v0
	v_mov_b32_e32 v49, v0
	v_mov_b32_e32 v50, v0
	v_mov_b32_e32 v51, v0
	v_mov_b32_e32 v20, v0
	v_mov_b32_e32 v21, v0
	v_mov_b32_e32 v22, v0
	v_mov_b32_e32 v23, v0
	v_mov_b32_e32 v52, v0
	v_mov_b32_e32 v53, v0
	v_mov_b32_e32 v54, v0
	v_mov_b32_e32 v55, v0
	v_mov_b32_e32 v24, v0
	v_mov_b32_e32 v25, v0
	v_mov_b32_e32 v26, v0
	v_mov_b32_e32 v27, v0
	v_mov_b32_e32 v56, v0
	v_mov_b32_e32 v57, v0
	v_mov_b32_e32 v58, v0
	v_mov_b32_e32 v59, v0
	v_mov_b32_e32 v28, v0
	v_mov_b32_e32 v29, v0
	v_mov_b32_e32 v30, v0
	v_mov_b32_e32 v31, v0
	v_mov_b32_e32 v60, v0
	v_mov_b32_e32 v61, v0
	v_mov_b32_e32 v62, v0
	v_mov_b32_e32 v63, v0
	v_mov_b32_e32 v80, v0
	v_mov_b32_e32 v81, v0
	v_mov_b32_e32 v82, v0
	v_mov_b32_e32 v83, v0
	v_mov_b32_e32 v112, v0
	v_mov_b32_e32 v113, v0
	v_mov_b32_e32 v114, v0
	v_mov_b32_e32 v115, v0
	v_mov_b32_e32 v84, v0
	v_mov_b32_e32 v85, v0
	v_mov_b32_e32 v86, v0
	v_mov_b32_e32 v87, v0
	v_mov_b32_e32 v116, v0
	v_mov_b32_e32 v117, v0
	v_mov_b32_e32 v118, v0
	v_mov_b32_e32 v119, v0
	v_mov_b32_e32 v88, v0
	v_mov_b32_e32 v89, v0
	v_mov_b32_e32 v90, v0
	v_mov_b32_e32 v91, v0
	v_mov_b32_e32 v120, v0
	v_mov_b32_e32 v121, v0
	v_mov_b32_e32 v122, v0
	v_mov_b32_e32 v123, v0
	v_mov_b32_e32 v92, v0
	v_mov_b32_e32 v93, v0
	v_mov_b32_e32 v94, v0
	v_mov_b32_e32 v95, v0
	v_mov_b32_e32 v124, v0
	v_mov_b32_e32 v125, v0
	v_mov_b32_e32 v126, v0
	v_mov_b32_e32 v127, v0
	.p2align	6

;     __device__ bool next(int i, Unit& u) const { Unit t; if (!T.next(i / 3, t)) return false; u.pm = t.pm; u.pn = (i % 3) * 4 + t.pn; return true; }
;     __device__ __forceinline__ size_t aoff(const Unit& u) const { const int br = u.pn >> 2; return (size_t)(br == 0 ? 0 : (br == 1 ? 256 : 768)) * 2; }
;     __device__ __forceinline__ int nt(const Unit& u, int) const { return (u.pn >> 2) == 0 ? 4 : 8; }
; template <class Epi, class Sched, bool ALIGN_EPI = false, bool SP2 = false>
; __device__ __forceinline__ void gemm_phase(PG8_LAS unsigned char* lds, const Gemm g, const Sched& S, const Epi& E, const int lda) {
;     ...
;         const bool has_next = S.next(ui + 1, nxt);
;         const char* nA = has_next ? (const char*)gA + (size_t)nxt.pm * tstepA + S.aoff(nxt) : cA; const char* nB = has_next ? (const char*)gB + (size_t)nxt.pn * tstep : cB;
;         for (int t = 0; t < nt; t += 2) {
;             const bool last = (t == nt - 2);
;             const char* a1 = cA + (size_t)(t + 1) * kstep;
;             const char* a2 = last ? nA : cA + (size_t)(t + 2) * kstep; const char* b2 = last ? nB : cB + (size_t)(t + 2) * kstep;
;             const char* a3 = a2 + kstep; const char* b3 = b2 + kstep;
;     ...
; #pragma unroll
;         for (int a = 0; a < 2; ++a)
; #pragma unroll
;             for (int b = 0; b < 2; ++b)
; #pragma unroll
;                 for (int m = 0; m < 4; ++m)
; #pragma unroll
;                     for (int n = 0; n < 2; ++n) acc[a][b][m][n] = (f32x4){0.f, 0.f, 0.f, 0.f};
;         cur = nxt; cA = nA; cB = nB; ++ui; nt = S.nt(cur, K / BK);
.LBB0_638:
	s_ashr_i32 s55, s54, 31
	s_lshl_b64 s[24:25], s[54:55], 18
	s_add_u32 s56, s46, s24
	s_addc_u32 s57, s47, s25
	s_and_b64 s[24:25], s[42:43], exec
	s_cselect_b32 s55, s57, s61
	s_cselect_b32 s67, s56, s60
	s_add_i32 s68, s64, -2
	s_add_u32 s60, s60, 0x100
	v_mov_b32_e32 v0, 0
	s_addc_u32 s61, s61, 0
	s_mov_b32 s24, 0
	v_mov_b32_e32 v1, v0
	v_mov_b32_e32 v2, v0
	v_mov_b32_e32 v3, v0
	v_mov_b32_e32 v4, v0
	v_mov_b32_e32 v5, v0
	v_mov_b32_e32 v6, v0
	v_mov_b32_e32 v7, v0
	v_mov_b32_e32 v8, v0
	v_mov_b32_e32 v9, v0
	v_mov_b32_e32 v10, v0
	v_mov_b32_e32 v11, v0
	v_mov_b32_e32 v16, v0
	v_mov_b32_e32 v17, v0
	v_mov_b32_e32 v18, v0
	v_mov_b32_e32 v19, v0
	v_mov_b32_e32 v24, v0
	v_mov_b32_e32 v25, v0
	v_mov_b32_e32 v26, v0
	v_mov_b32_e32 v27, v0
	v_mov_b32_e32 v32, v0
	v_mov_b32_e32 v33, v0
	v_mov_b32_e32 v34, v0
	v_mov_b32_e32 v35, v0
	v_mov_b32_e32 v40, v0
	v_mov_b32_e32 v41, v0
	v_mov_b32_e32 v42, v0
	v_mov_b32_e32 v43, v0
	v_mov_b32_e32 v48, v0
	v_mov_b32_e32 v49, v0
	v_mov_b32_e32 v50, v0
	v_mov_b32_e32 v51, v0
	v_mov_b32_e32 v12, v0
	v_mov_b32_e32 v13, v0
	v_mov_b32_e32 v14, v0
	v_mov_b32_e32 v15, v0
	v_mov_b32_e32 v20, v0
	v_mov_b32_e32 v21, v0
	v_mov_b32_e32 v22, v0
	v_mov_b32_e32 v23, v0
	v_mov_b32_e32 v28, v0
	v_mov_b32_e32 v29, v0
	v_mov_b32_e32 v30, v0
	v_mov_b32_e32 v31, v0
	v_mov_b32_e32 v36, v0
	v_mov_b32_e32 v37, v0
	v_mov_b32_e32 v38, v0
	v_mov_b32_e32 v39, v0
	v_mov_b32_e32 v44, v0
	v_mov_b32_e32 v45, v0
	v_mov_b32_e32 v46, v0
	v_mov_b32_e32 v47, v0
	v_mov_b32_e32 v52, v0
	v_mov_b32_e32 v53, v0
	v_mov_b32_e32 v54, v0
	v_mov_b32_e32 v55, v0
	v_mov_b32_e32 v56, v0
	v_mov_b32_e32 v57, v0
	v_mov_b32_e32 v58, v0
	v_mov_b32_e32 v59, v0
	v_mov_b32_e32 v60, v0
	v_mov_b32_e32 v61, v0
	v_mov_b32_e32 v62, v0
	v_mov_b32_e32 v63, v0
	v_mov_b32_e32 v64, v0
	v_mov_b32_e32 v65, v0
	v_mov_b32_e32 v66, v0
	v_mov_b32_e32 v67, v0
	v_mov_b32_e32 v68, v0
	v_mov_b32_e32 v69, v0
	v_mov_b32_e32 v70, v0
	v_mov_b32_e32 v71, v0
	v_mov_b32_e32 v72, v0
	v_mov_b32_e32 v73, v0
	v_mov_b32_e32 v74, v0
	v_mov_b32_e32 v75, v0
	v_mov_b32_e32 v80, v0
	v_mov_b32_e32 v81, v0
	v_mov_b32_e32 v82, v0
	v_mov_b32_e32 v83, v0
	v_mov_b32_e32 v88, v0
	v_mov_b32_e32 v89, v0
	v_mov_b32_e32 v90, v0
	v_mov_b32_e32 v91, v0
	v_mov_b32_e32 v96, v0
	v_mov_b32_e32 v97, v0
	v_mov_b32_e32 v98, v0
	v_mov_b32_e32 v99, v0
	v_mov_b32_e32 v104, v0
	v_mov_b32_e32 v105, v0
	v_mov_b32_e32 v106, v0
	v_mov_b32_e32 v107, v0
	v_mov_b32_e32 v112, v0
	v_mov_b32_e32 v113, v0
	v_mov_b32_e32 v114, v0
	v_mov_b32_e32 v115, v0
	v_mov_b32_e32 v76, v0
	v_mov_b32_e32 v77, v0
	v_mov_b32_e32 v78, v0
	v_mov_b32_e32 v79, v0
	v_mov_b32_e32 v84, v0
	v_mov_b32_e32 v85, v0
	v_mov_b32_e32 v86, v0
	v_mov_b32_e32 v87, v0
	v_mov_b32_e32 v92, v0
	v_mov_b32_e32 v93, v0
	v_mov_b32_e32 v94, v0
	v_mov_b32_e32 v95, v0
	v_mov_b32_e32 v100, v0
	v_mov_b32_e32 v101, v0
	v_mov_b32_e32 v102, v0
	v_mov_b32_e32 v103, v0
	v_mov_b32_e32 v108, v0
	v_mov_b32_e32 v109, v0
	v_mov_b32_e32 v110, v0
	v_mov_b32_e32 v111, v0
	v_mov_b32_e32 v116, v0
	v_mov_b32_e32 v117, v0
	v_mov_b32_e32 v118, v0
	v_mov_b32_e32 v119, v0
	v_mov_b32_e32 v120, v0
	v_mov_b32_e32 v121, v0
	v_mov_b32_e32 v122, v0
	v_mov_b32_e32 v123, v0
	v_mov_b32_e32 v124, v0
	v_mov_b32_e32 v125, v0
	v_mov_b32_e32 v126, v0
	v_mov_b32_e32 v127, v0
	.p2align	6

;     __device__ bool next(int i, Unit& u) const { Unit t; if (!T.next(i / 3, t)) return false; u.pm = t.pm; u.pn = (i % 3) * 4 + t.pn; return true; }
;     __device__ __forceinline__ size_t aoff(const Unit& u) const { const int br = u.pn >> 2; return (size_t)(br == 0 ? 0 : (br == 1 ? 256 : 768)) * 2; }
;     __device__ __forceinline__ int nt(const Unit& u, int) const { return (u.pn >> 2) == 0 ? 4 : 8; }
; template <class Epi, class Sched, bool ALIGN_EPI = false, bool SP2 = false>
; __device__ __forceinline__ void gemm_phase(PG8_LAS unsigned char* lds, const Gemm g, const Sched& S, const Epi& E, const int lda) {
;     ...
;         const bool has_next = S.next(ui + 1, nxt);
;         const char* nA = has_next ? (const char*)gA + (size_t)nxt.pm * tstepA + S.aoff(nxt) : cA; const char* nB = has_next ? (const char*)gB + (size_t)nxt.pn * tstep : cB;
;         for (int t = 0; t < nt; t += 2) {
;             const bool last = (t == nt - 2);
;             const char* a1 = cA + (size_t)(t + 1) * kstep;
;             const char* a2 = last ? nA : cA + (size_t)(t + 2) * kstep; const char* b2 = last ? nB : cB + (size_t)(t + 2) * kstep;
;             const char* a3 = a2 + kstep; const char* b3 = b2 + kstep;
;     ...
; #pragma unroll
;         for (int a = 0; a < 2; ++a)
; #pragma unroll
;             for (int b = 0; b < 2; ++b)
; #pragma unroll
;                 for (int m = 0; m < 4; ++m)
; #pragma unroll
;                     for (int n = 0; n < 2; ++n) acc[a][b][m][n] = (f32x4){0.f, 0.f, 0.f, 0.f};
;         cur = nxt; cA = nA; cB = nB; ++ui; nt = S.nt(cur, K / BK);
.LBB0_658:
	s_ashr_i32 s55, s54, 31
	s_lshl_b64 s[22:23], s[54:55], 19
	s_add_u32 s60, s44, s22
	s_addc_u32 s61, s45, s23
	s_and_b64 s[22:23], s[40:41], exec
	s_cselect_b32 s21, s61, s69
	s_cselect_b32 s22, s60, s68
	s_ashr_i32 s57, s56, 31
	s_lshl_b64 s[24:25], s[56:57], 19
	s_add_u32 s62, s46, s24
	s_addc_u32 s63, s47, s25
	s_and_b64 s[24:25], s[40:41], exec
	s_cselect_b32 s23, s63, s67
	s_cselect_b32 s24, s62, s66
	s_add_u32 s25, s66, 0x100
	s_addc_u32 s26, s67, 0
	s_add_u32 s66, s68, 0x40080
	v_mov_b32_e32 v0, 0
	s_addc_u32 s67, s69, 0
	s_mov_b32 s27, -2
	v_mov_b32_e32 v1, v0
	v_mov_b32_e32 v2, v0
	v_mov_b32_e32 v3, v0
	v_mov_b32_e32 v4, v0
	v_mov_b32_e32 v5, v0
	v_mov_b32_e32 v6, v0
	v_mov_b32_e32 v7, v0
	v_mov_b32_e32 v16, v0
	v_mov_b32_e32 v17, v0
	v_mov_b32_e32 v18, v0
	v_mov_b32_e32 v19, v0
	s_waitcnt vmcnt(0)
	v_mov_b32_e32 v20, v0
	v_mov_b32_e32 v21, v0
	v_mov_b32_e32 v22, v0
	v_mov_b32_e32 v23, v0
	v_mov_b32_e32 v32, v0
	v_mov_b32_e32 v33, v0
	v_mov_b32_e32 v34, v0
	v_mov_b32_e32 v35, v0
	v_mov_b32_e32 v36, v0
	v_mov_b32_e32 v37, v0
	v_mov_b32_e32 v38, v0
	v_mov_b32_e32 v39, v0
	v_mov_b32_e32 v48, v0
	v_mov_b32_e32 v49, v0
	v_mov_b32_e32 v50, v0
	v_mov_b32_e32 v51, v0
	v_mov_b32_e32 v52, v0
	v_mov_b32_e32 v53, v0
	v_mov_b32_e32 v54, v0
	v_mov_b32_e32 v55, v0
	v_mov_b32_e32 v8, v0
	v_mov_b32_e32 v9, v0
	v_mov_b32_e32 v10, v0
	v_mov_b32_e32 v11, v0
	v_mov_b32_e32 v12, v0
	v_mov_b32_e32 v13, v0
	v_mov_b32_e32 v14, v0
	v_mov_b32_e32 v15, v0
	v_mov_b32_e32 v24, v0
	v_mov_b32_e32 v25, v0
	v_mov_b32_e32 v26, v0
	v_mov_b32_e32 v27, v0
	v_mov_b32_e32 v28, v0
	v_mov_b32_e32 v29, v0
	v_mov_b32_e32 v30, v0
	v_mov_b32_e32 v31, v0
	v_mov_b32_e32 v40, v0
	v_mov_b32_e32 v41, v0
	v_mov_b32_e32 v42, v0
	v_mov_b32_e32 v43, v0
	v_mov_b32_e32 v44, v0
	v_mov_b32_e32 v45, v0
	v_mov_b32_e32 v46, v0
	v_mov_b32_e32 v47, v0
	v_mov_b32_e32 v56, v0
	v_mov_b32_e32 v57, v0
	v_mov_b32_e32 v58, v0
	v_mov_b32_e32 v59, v0
	v_mov_b32_e32 v60, v0
	v_mov_b32_e32 v61, v0
	v_mov_b32_e32 v62, v0
	v_mov_b32_e32 v63, v0
	v_mov_b32_e32 v64, v0
	v_mov_b32_e32 v65, v0
	v_mov_b32_e32 v66, v0
	v_mov_b32_e32 v67, v0
	v_mov_b32_e32 v68, v0
	v_mov_b32_e32 v69, v0
	v_mov_b32_e32 v70, v0
	v_mov_b32_e32 v71, v0
	v_mov_b32_e32 v80, v0
	v_mov_b32_e32 v81, v0
	v_mov_b32_e32 v82, v0
	v_mov_b32_e32 v83, v0
	v_mov_b32_e32 v84, v0
	v_mov_b32_e32 v85, v0
	v_mov_b32_e32 v86, v0
	v_mov_b32_e32 v87, v0
	v_mov_b32_e32 v104, v0
	v_mov_b32_e32 v105, v0
	v_mov_b32_e32 v106, v0
	v_mov_b32_e32 v107, v0
	v_mov_b32_e32 v112, v0
	v_mov_b32_e32 v113, v0
	v_mov_b32_e32 v114, v0
	v_mov_b32_e32 v115, v0
	v_mov_b32_e32 v136, v0
	v_mov_b32_e32 v137, v0
	v_mov_b32_e32 v138, v0
	v_mov_b32_e32 v139, v0
	v_mov_b32_e32 v148, v0
	v_mov_b32_e32 v149, v0
	v_mov_b32_e32 v150, v0
	v_mov_b32_e32 v151, v0
	v_mov_b32_e32 v72, v0
	v_mov_b32_e32 v73, v0
	v_mov_b32_e32 v74, v0
	v_mov_b32_e32 v75, v0
	v_mov_b32_e32 v76, v0
	v_mov_b32_e32 v77, v0
	v_mov_b32_e32 v78, v0
	v_mov_b32_e32 v79, v0
	v_mov_b32_e32 v88, v0
	v_mov_b32_e32 v89, v0
	v_mov_b32_e32 v90, v0
	v_mov_b32_e32 v91, v0
	v_mov_b32_e32 v96, v0
	v_mov_b32_e32 v97, v0
	v_mov_b32_e32 v98, v0
	v_mov_b32_e32 v99, v0
	v_mov_b32_e32 v120, v0
	v_mov_b32_e32 v121, v0
	v_mov_b32_e32 v122, v0
	v_mov_b32_e32 v123, v0
	v_mov_b32_e32 v132, v0
	v_mov_b32_e32 v133, v0
	v_mov_b32_e32 v134, v0
	v_mov_b32_e32 v135, v0
	v_mov_b32_e32 v156, v0
	v_mov_b32_e32 v157, v0
	v_mov_b32_e32 v158, v0
	v_mov_b32_e32 v159, v0
	v_mov_b32_e32 v164, v0
	v_mov_b32_e32 v165, v0
	v_mov_b32_e32 v166, v0
	v_mov_b32_e32 v167, v0
	.p2align	6

;     __device__ bool next(int i, Unit& u) const { Unit t; if (!T.next(i / 3, t)) return false; u.pm = t.pm; u.pn = (i % 3) * 4 + t.pn; return true; }
;     __device__ __forceinline__ size_t aoff(const Unit& u) const { const int br = u.pn >> 2; return (size_t)(br == 0 ? 0 : (br == 1 ? 256 : 768)) * 2; }
;     __device__ __forceinline__ int nt(const Unit& u, int) const { return (u.pn >> 2) == 0 ? 4 : 8; }
; template <class Epi, class Sched, bool ALIGN_EPI = false, bool SP2 = false>
; __device__ __forceinline__ void gemm_phase(PG8_LAS unsigned char* lds, const Gemm g, const Sched& S, const Epi& E, const int lda) {
;     ...
;         const bool has_next = S.next(ui + 1, nxt);
;         const char* nA = has_next ? (const char*)gA + (size_t)nxt.pm * tstepA + S.aoff(nxt) : cA; const char* nB = has_next ? (const char*)gB + (size_t)nxt.pn * tstep : cB;
;         for (int t = 0; t < nt; t += 2) {
;             const bool last = (t == nt - 2);
;             const char* a1 = cA + (size_t)(t + 1) * kstep;
;             const char* a2 = last ? nA : cA + (size_t)(t + 2) * kstep; const char* b2 = last ? nB : cB + (size_t)(t + 2) * kstep;
;             const char* a3 = a2 + kstep; const char* b3 = b2 + kstep;
;     ...
; #pragma unroll
;         for (int a = 0; a < 2; ++a)
; #pragma unroll
;             for (int b = 0; b < 2; ++b)
; #pragma unroll
;                 for (int m = 0; m < 4; ++m)
; #pragma unroll
;                     for (int n = 0; n < 2; ++n) acc[a][b][m][n] = (f32x4){0.f, 0.f, 0.f, 0.f};
;         cur = nxt; cA = nA; cB = nB; ++ui; nt = S.nt(cur, K / BK);
.LBB0_764:
	s_ashr_i32 s57, s56, 31
	s_lshl_b64 s[24:25], s[56:57], 19
	s_add_u32 s60, s46, s24
	s_addc_u32 s61, s47, s25
	s_and_b64 s[24:25], s[42:43], exec
	s_cselect_b32 s57, s61, s63
	s_cselect_b32 s68, s60, s62
	s_add_u32 s62, s62, 0x100
	v_mov_b32_e32 v0, 0
	s_addc_u32 s63, s63, 0
	s_mov_b32 s69, -2
	v_mov_b32_e32 v1, v0
	v_mov_b32_e32 v2, v0
	v_mov_b32_e32 v3, v0
	v_mov_b32_e32 v4, v0
	v_mov_b32_e32 v5, v0
	v_mov_b32_e32 v6, v0
	v_mov_b32_e32 v7, v0
	v_mov_b32_e32 v8, v0
	v_mov_b32_e32 v9, v0
	v_mov_b32_e32 v10, v0
	v_mov_b32_e32 v11, v0
	v_mov_b32_e32 v12, v0
	v_mov_b32_e32 v13, v0
	v_mov_b32_e32 v14, v0
	v_mov_b32_e32 v15, v0
	v_mov_b32_e32 v20, v0
	v_mov_b32_e32 v21, v0
	v_mov_b32_e32 v22, v0
	v_mov_b32_e32 v23, v0
	v_mov_b32_e32 v24, v0
	v_mov_b32_e32 v25, v0
	v_mov_b32_e32 v26, v0
	v_mov_b32_e32 v27, v0
	v_mov_b32_e32 v32, v0
	v_mov_b32_e32 v33, v0
	v_mov_b32_e32 v34, v0
	v_mov_b32_e32 v35, v0
	v_mov_b32_e32 v40, v0
	v_mov_b32_e32 v41, v0
	v_mov_b32_e32 v42, v0
	v_mov_b32_e32 v43, v0
	v_mov_b32_e32 v16, v0
	v_mov_b32_e32 v17, v0
	v_mov_b32_e32 v18, v0
	v_mov_b32_e32 v19, v0
	v_mov_b32_e32 v28, v0
	v_mov_b32_e32 v29, v0
	v_mov_b32_e32 v30, v0
	v_mov_b32_e32 v31, v0
	v_mov_b32_e32 v36, v0
	v_mov_b32_e32 v37, v0
	v_mov_b32_e32 v38, v0
	v_mov_b32_e32 v39, v0
	v_mov_b32_e32 v44, v0
	v_mov_b32_e32 v45, v0
	v_mov_b32_e32 v46, v0
	v_mov_b32_e32 v47, v0
	v_mov_b32_e32 v48, v0
	v_mov_b32_e32 v49, v0
	v_mov_b32_e32 v50, v0
	v_mov_b32_e32 v51, v0
	v_mov_b32_e32 v52, v0
	v_mov_b32_e32 v53, v0
	v_mov_b32_e32 v54, v0
	v_mov_b32_e32 v55, v0
	v_mov_b32_e32 v56, v0
	v_mov_b32_e32 v57, v0
	v_mov_b32_e32 v58, v0
	v_mov_b32_e32 v59, v0
	v_mov_b32_e32 v60, v0
	v_mov_b32_e32 v61, v0
	v_mov_b32_e32 v62, v0
	v_mov_b32_e32 v63, v0
	v_mov_b32_e32 v64, v0
	v_mov_b32_e32 v65, v0
	v_mov_b32_e32 v66, v0
	v_mov_b32_e32 v67, v0
	v_mov_b32_e32 v68, v0
	v_mov_b32_e32 v69, v0
	v_mov_b32_e32 v70, v0
	v_mov_b32_e32 v71, v0
	v_mov_b32_e32 v72, v0
	v_mov_b32_e32 v73, v0
	v_mov_b32_e32 v74, v0
	v_mov_b32_e32 v75, v0
	v_mov_b32_e32 v76, v0
	v_mov_b32_e32 v77, v0
	v_mov_b32_e32 v78, v0
	v_mov_b32_e32 v79, v0
	v_mov_b32_e32 v84, v0
	v_mov_b32_e32 v85, v0
	v_mov_b32_e32 v86, v0
	v_mov_b32_e32 v87, v0
	v_mov_b32_e32 v88, v0
	v_mov_b32_e32 v89, v0
	v_mov_b32_e32 v90, v0
	v_mov_b32_e32 v91, v0
	v_mov_b32_e32 v96, v0
	v_mov_b32_e32 v97, v0
	v_mov_b32_e32 v98, v0
	v_mov_b32_e32 v99, v0
	v_mov_b32_e32 v104, v0
	v_mov_b32_e32 v105, v0
	v_mov_b32_e32 v106, v0
	v_mov_b32_e32 v107, v0
	v_mov_b32_e32 v80, v0
	v_mov_b32_e32 v81, v0
	v_mov_b32_e32 v82, v0
	v_mov_b32_e32 v83, v0
	v_mov_b32_e32 v92, v0
	v_mov_b32_e32 v93, v0
	v_mov_b32_e32 v94, v0
	v_mov_b32_e32 v95, v0
	v_mov_b32_e32 v100, v0
	v_mov_b32_e32 v101, v0
	v_mov_b32_e32 v102, v0
	v_mov_b32_e32 v103, v0
	v_mov_b32_e32 v108, v0
	v_mov_b32_e32 v109, v0
	v_mov_b32_e32 v110, v0
	v_mov_b32_e32 v111, v0
	v_mov_b32_e32 v112, v0
	v_mov_b32_e32 v113, v0
	v_mov_b32_e32 v114, v0
	v_mov_b32_e32 v115, v0
	v_mov_b32_e32 v116, v0
	v_mov_b32_e32 v117, v0
	v_mov_b32_e32 v118, v0
	v_mov_b32_e32 v119, v0
	v_mov_b32_e32 v120, v0
	v_mov_b32_e32 v121, v0
	v_mov_b32_e32 v122, v0
	v_mov_b32_e32 v123, v0
	v_mov_b32_e32 v124, v0
	v_mov_b32_e32 v125, v0
	v_mov_b32_e32 v126, v0
	v_mov_b32_e32 v127, v0
	.p2align	6

;     __device__ bool next(int i, Unit& u) const { Unit t; if (!T.next(i / 3, t)) return false; u.pm = t.pm; u.pn = (i % 3) * 4 + t.pn; return true; }
;     __device__ __forceinline__ size_t aoff(const Unit& u) const { const int br = u.pn >> 2; return (size_t)(br == 0 ? 0 : (br == 1 ? 256 : 768)) * 2; }
;     __device__ __forceinline__ int nt(const Unit& u, int) const { return (u.pn >> 2) == 0 ? 4 : 8; }
; template <class Epi, class Sched, bool ALIGN_EPI = false, bool SP2 = false>
; __device__ __forceinline__ void gemm_phase(PG8_LAS unsigned char* lds, const Gemm g, const Sched& S, const Epi& E, const int lda) {
;     ...
;         const bool has_next = S.next(ui + 1, nxt);
;         const char* nA = has_next ? (const char*)gA + (size_t)nxt.pm * tstepA + S.aoff(nxt) : cA; const char* nB = has_next ? (const char*)gB + (size_t)nxt.pn * tstep : cB;
;         for (int t = 0; t < nt; t += 2) {
;             const bool last = (t == nt - 2);
;             const char* a1 = cA + (size_t)(t + 1) * kstep;
;             const char* a2 = last ? nA : cA + (size_t)(t + 2) * kstep; const char* b2 = last ? nB : cB + (size_t)(t + 2) * kstep;
;             const char* a3 = a2 + kstep; const char* b3 = b2 + kstep;
;     ...
; #pragma unroll
;         for (int a = 0; a < 2; ++a)
; #pragma unroll
;             for (int b = 0; b < 2; ++b)
; #pragma unroll
;                 for (int m = 0; m < 4; ++m)
; #pragma unroll
;                     for (int n = 0; n < 2; ++n) acc[a][b][m][n] = (f32x4){0.f, 0.f, 0.f, 0.f};
;         cur = nxt; cA = nA; cB = nB; ++ui; nt = S.nt(cur, K / BK);
.LBB0_892:
	s_ashr_i32 s55, s54, 31
	s_lshl_b64 s[24:25], s[54:55], 19
	s_add_u32 s56, s42, s24
	s_addc_u32 s57, s43, s25
	s_and_b64 s[24:25], s[40:41], exec
	s_cselect_b32 s55, s57, s65
	s_cselect_b32 s71, s56, s64
	s_ashr_i32 s53, s52, 31
	s_lshl_b64 s[24:25], s[52:53], 19
	s_add_u32 s60, s44, s24
	s_addc_u32 s61, s45, s25
	s_and_b64 s[24:25], s[40:41], exec
	s_cselect_b32 s53, s61, s63
	s_cselect_b32 s24, s60, s62
	s_add_u32 s25, s62, 0x100
	s_addc_u32 s26, s63, 0
	s_add_u32 s62, s64, 0x40080
	v_mov_b32_e32 v0, 0
	s_addc_u32 s63, s65, 0
	s_mov_b32 s27, -2
	v_mov_b32_e32 v1, v0
	v_mov_b32_e32 v2, v0
	v_mov_b32_e32 v3, v0
	v_mov_b32_e32 v8, v0
	v_mov_b32_e32 v9, v0
	v_mov_b32_e32 v10, v0
	v_mov_b32_e32 v11, v0
	v_mov_b32_e32 v16, v0
	v_mov_b32_e32 v17, v0
	v_mov_b32_e32 v18, v0
	v_mov_b32_e32 v19, v0
	v_mov_b32_e32 v24, v0
	v_mov_b32_e32 v25, v0
	v_mov_b32_e32 v26, v0
	v_mov_b32_e32 v27, v0
	v_mov_b32_e32 v32, v0
	v_mov_b32_e32 v33, v0
	v_mov_b32_e32 v34, v0
	v_mov_b32_e32 v35, v0
	v_mov_b32_e32 v40, v0
	v_mov_b32_e32 v41, v0
	v_mov_b32_e32 v42, v0
	v_mov_b32_e32 v43, v0
	v_mov_b32_e32 v48, v0
	v_mov_b32_e32 v49, v0
	v_mov_b32_e32 v50, v0
	v_mov_b32_e32 v51, v0
	v_mov_b32_e32 v56, v0
	v_mov_b32_e32 v57, v0
	v_mov_b32_e32 v58, v0
	v_mov_b32_e32 v59, v0
	v_mov_b32_e32 v4, v0
	v_mov_b32_e32 v5, v0
	v_mov_b32_e32 v6, v0
	v_mov_b32_e32 v7, v0
	v_mov_b32_e32 v12, v0
	v_mov_b32_e32 v13, v0
	v_mov_b32_e32 v14, v0
	v_mov_b32_e32 v15, v0
	v_mov_b32_e32 v20, v0
	v_mov_b32_e32 v21, v0
	v_mov_b32_e32 v22, v0
	v_mov_b32_e32 v23, v0
	v_mov_b32_e32 v28, v0
	v_mov_b32_e32 v29, v0
	v_mov_b32_e32 v30, v0
	v_mov_b32_e32 v31, v0
	v_mov_b32_e32 v36, v0
	v_mov_b32_e32 v37, v0
	v_mov_b32_e32 v38, v0
	v_mov_b32_e32 v39, v0
	v_mov_b32_e32 v44, v0
	v_mov_b32_e32 v45, v0
	v_mov_b32_e32 v46, v0
	v_mov_b32_e32 v47, v0
	v_mov_b32_e32 v52, v0
	v_mov_b32_e32 v53, v0
	v_mov_b32_e32 v54, v0
	v_mov_b32_e32 v55, v0
	v_mov_b32_e32 v60, v0
	v_mov_b32_e32 v61, v0
	v_mov_b32_e32 v62, v0
	v_mov_b32_e32 v63, v0
	v_mov_b32_e32 v64, v0
	v_mov_b32_e32 v65, v0
	v_mov_b32_e32 v66, v0
	v_mov_b32_e32 v67, v0
	v_mov_b32_e32 v72, v0
	v_mov_b32_e32 v73, v0
	v_mov_b32_e32 v74, v0
	v_mov_b32_e32 v75, v0
	v_mov_b32_e32 v80, v0
	v_mov_b32_e32 v81, v0
	v_mov_b32_e32 v82, v0
	v_mov_b32_e32 v83, v0
	v_mov_b32_e32 v88, v0
	v_mov_b32_e32 v89, v0
	v_mov_b32_e32 v90, v0
	v_mov_b32_e32 v91, v0
	v_mov_b32_e32 v96, v0
	v_mov_b32_e32 v97, v0
	v_mov_b32_e32 v98, v0
	v_mov_b32_e32 v99, v0
	v_mov_b32_e32 v104, v0
	v_mov_b32_e32 v105, v0
	v_mov_b32_e32 v106, v0
	v_mov_b32_e32 v107, v0
	v_mov_b32_e32 v112, v0
	v_mov_b32_e32 v113, v0
	v_mov_b32_e32 v114, v0
	v_mov_b32_e32 v115, v0
	v_mov_b32_e32 v120, v0
	v_mov_b32_e32 v121, v0
	v_mov_b32_e32 v122, v0
	v_mov_b32_e32 v123, v0
	v_mov_b32_e32 v68, v0
	v_mov_b32_e32 v69, v0
	v_mov_b32_e32 v70, v0
	v_mov_b32_e32 v71, v0
	v_mov_b32_e32 v76, v0
	v_mov_b32_e32 v77, v0
	v_mov_b32_e32 v78, v0
	v_mov_b32_e32 v79, v0
	v_mov_b32_e32 v84, v0
	v_mov_b32_e32 v85, v0
	v_mov_b32_e32 v86, v0
	v_mov_b32_e32 v87, v0
	v_mov_b32_e32 v92, v0
	v_mov_b32_e32 v93, v0
	v_mov_b32_e32 v94, v0
	v_mov_b32_e32 v95, v0
	v_mov_b32_e32 v100, v0
	v_mov_b32_e32 v101, v0
	v_mov_b32_e32 v102, v0
	v_mov_b32_e32 v103, v0
	v_mov_b32_e32 v108, v0
	v_mov_b32_e32 v109, v0
	v_mov_b32_e32 v110, v0
	v_mov_b32_e32 v111, v0
	v_mov_b32_e32 v116, v0
	v_mov_b32_e32 v117, v0
	v_mov_b32_e32 v118, v0
	v_mov_b32_e32 v119, v0
	v_mov_b32_e32 v124, v0
	v_mov_b32_e32 v125, v0
	v_mov_b32_e32 v126, v0
	v_mov_b32_e32 v127, v0
	.p2align	6

;     __device__ __forceinline__ int nt(const Unit& u, int) const { return (u.pn >> 2) == 0 ? 4 : 8; }
; template <class Epi, class Sched, bool ALIGN_EPI = false, bool SP2 = false>
; __device__ __forceinline__ void gemm_phase(PG8_LAS unsigned char* lds, const Gemm g, const Sched& S, const Epi& E, const int lda) {
;     ...
; #pragma unroll
;         for (int a = 0; a < 2; ++a)
; #pragma unroll
;             for (int b = 0; b < 2; ++b)
; #pragma unroll
;                 for (int m = 0; m < 4; ++m)
; #pragma unroll
;                     for (int n = 0; n < 2; ++n) acc[a][b][m][n] = (f32x4){0.f, 0.f, 0.f, 0.f};
;         cur = nxt; cA = nA; cB = nB; ++ui; nt = S.nt(cur, K / BK);
.LBB0_968:
	s_add_u32 s63, s52, 0x100
	v_mov_b32_e32 v0, 0
	s_addc_u32 s64, s53, 0
	s_mov_b32 s65, -2
	v_mov_b32_e32 v1, v0
	v_mov_b32_e32 v2, v0
	v_mov_b32_e32 v3, v0
	v_mov_b32_e32 v4, v0
	v_mov_b32_e32 v5, v0
	v_mov_b32_e32 v6, v0
	v_mov_b32_e32 v7, v0
	v_mov_b32_e32 v8, v0
	v_mov_b32_e32 v9, v0
	v_mov_b32_e32 v10, v0
	v_mov_b32_e32 v11, v0
	v_mov_b32_e32 v12, v0
	v_mov_b32_e32 v13, v0
	v_mov_b32_e32 v14, v0
	v_mov_b32_e32 v15, v0
	v_mov_b32_e32 v20, v0
	v_mov_b32_e32 v21, v0
	v_mov_b32_e32 v22, v0
	v_mov_b32_e32 v23, v0
	v_mov_b32_e32 v24, v0
	v_mov_b32_e32 v25, v0
	v_mov_b32_e32 v26, v0
	v_mov_b32_e32 v27, v0
	v_mov_b32_e32 v32, v0
	v_mov_b32_e32 v33, v0
	v_mov_b32_e32 v34, v0
	v_mov_b32_e32 v35, v0
	v_mov_b32_e32 v40, v0
	v_mov_b32_e32 v41, v0
	v_mov_b32_e32 v42, v0
	v_mov_b32_e32 v43, v0
	v_mov_b32_e32 v16, v0
	v_mov_b32_e32 v17, v0
	v_mov_b32_e32 v18, v0
	v_mov_b32_e32 v19, v0
	v_mov_b32_e32 v28, v0
	v_mov_b32_e32 v29, v0
	v_mov_b32_e32 v30, v0
	v_mov_b32_e32 v31, v0
	v_mov_b32_e32 v36, v0
	v_mov_b32_e32 v37, v0
	v_mov_b32_e32 v38, v0
	v_mov_b32_e32 v39, v0
	v_mov_b32_e32 v44, v0
	v_mov_b32_e32 v45, v0
	v_mov_b32_e32 v46, v0
	v_mov_b32_e32 v47, v0
	v_mov_b32_e32 v48, v0
	v_mov_b32_e32 v49, v0
	v_mov_b32_e32 v50, v0
	v_mov_b32_e32 v51, v0
	v_mov_b32_e32 v52, v0
	v_mov_b32_e32 v53, v0
	v_mov_b32_e32 v54, v0
	v_mov_b32_e32 v55, v0
	v_mov_b32_e32 v56, v0
	v_mov_b32_e32 v57, v0
	v_mov_b32_e32 v58, v0
	v_mov_b32_e32 v59, v0
	v_mov_b32_e32 v60, v0
	v_mov_b32_e32 v61, v0
	v_mov_b32_e32 v62, v0
	v_mov_b32_e32 v63, v0
	v_mov_b32_e32 v64, v0
	v_mov_b32_e32 v65, v0
	v_mov_b32_e32 v66, v0
	v_mov_b32_e32 v67, v0
	v_mov_b32_e32 v68, v0
	v_mov_b32_e32 v69, v0
	v_mov_b32_e32 v70, v0
	v_mov_b32_e32 v71, v0
	v_mov_b32_e32 v72, v0
	v_mov_b32_e32 v73, v0
	v_mov_b32_e32 v74, v0
	v_mov_b32_e32 v75, v0
	v_mov_b32_e32 v76, v0
	v_mov_b32_e32 v77, v0
	v_mov_b32_e32 v78, v0
	v_mov_b32_e32 v79, v0
	v_mov_b32_e32 v84, v0
	v_mov_b32_e32 v85, v0
	v_mov_b32_e32 v86, v0
	v_mov_b32_e32 v87, v0
	v_mov_b32_e32 v88, v0
	v_mov_b32_e32 v89, v0
	v_mov_b32_e32 v90, v0
	v_mov_b32_e32 v91, v0
	v_mov_b32_e32 v96, v0
	v_mov_b32_e32 v97, v0
	v_mov_b32_e32 v98, v0
	v_mov_b32_e32 v99, v0
	v_mov_b32_e32 v104, v0
	v_mov_b32_e32 v105, v0
	v_mov_b32_e32 v106, v0
	v_mov_b32_e32 v107, v0
	v_mov_b32_e32 v80, v0
	v_mov_b32_e32 v81, v0
	v_mov_b32_e32 v82, v0
	v_mov_b32_e32 v83, v0
	v_mov_b32_e32 v92, v0
	v_mov_b32_e32 v93, v0
	v_mov_b32_e32 v94, v0
	v_mov_b32_e32 v95, v0
	v_mov_b32_e32 v100, v0
	v_mov_b32_e32 v101, v0
	v_mov_b32_e32 v102, v0
	v_mov_b32_e32 v103, v0
	v_mov_b32_e32 v108, v0
	v_mov_b32_e32 v109, v0
	v_mov_b32_e32 v110, v0
	v_mov_b32_e32 v111, v0
	v_mov_b32_e32 v112, v0
	v_mov_b32_e32 v113, v0
	v_mov_b32_e32 v114, v0
	v_mov_b32_e32 v115, v0
	v_mov_b32_e32 v116, v0
	v_mov_b32_e32 v117, v0
	v_mov_b32_e32 v118, v0
	v_mov_b32_e32 v119, v0
	v_mov_b32_e32 v120, v0
	v_mov_b32_e32 v121, v0
	v_mov_b32_e32 v122, v0
	v_mov_b32_e32 v123, v0
	v_mov_b32_e32 v124, v0
	v_mov_b32_e32 v125, v0
	v_mov_b32_e32 v126, v0
	v_mov_b32_e32 v127, v0
	.p2align	6
